# phase-1 sample-row mini tiles moved to the workgroups whose last tile has the light epilogue
# speedup vs baseline: 1.0173x; 1.0173x over previous
.LBB0_576:
	s_min_i32 s9, s90, 0x80
	s_sub_i32 s15, s92, 0x80
	s_cmp_lt_i32 s15, 0
	s_cselect_b64 s[0:1], -1, 0
	s_cmp_ge_i32 s15, s9
	s_cselect_b64 s[2:3], -1, 0
	s_or_b64 s[0:1], s[0:1], s[2:3]
	s_and_b64 vcc, exec, s[0:1]
	s_cbranch_vccnz .LBB0_599
	v_lshlrev_b32_e32 v2, 4, v162
	v_and_b32_e32 v10, 0x70, v2
	v_mul_u32_u24_e32 v2, 0x88, v1
	v_lshl_add_u32 v26, v2, 1, v10
	v_lshlrev_b32_e32 v2, 4, v157
	s_movk_i32 s0, 0x110
	v_and_b32_e32 v3, 16, v156
	v_add3_u32 v4, v154, v155, 64
	v_or_b32_e32 v27, v154, v155
	v_mad_u32_u24 v29, v4, s0, v2
	v_or_b32_e32 v4, v3, v155
	v_mov_b32_e32 v11, 0
	v_mad_u32_u24 v28, v27, s0, v2
	v_mul_u32_u24_e32 v5, 0x110, v4
	v_mad_u32_u24 v30, v4, s0, v2
	v_lshl_or_b32 v31, v157, 2, v3
	v_bitop3_b32 v3, v154, 31, v155 bitop3:0xc8
	s_add_u32 s0, s84, 0x821e000
	v_lshl_add_u64 v[12:13], s[58:59], 0, v[10:11]
	v_lshl_add_u64 v[14:15], s[86:87], 0, v[10:11]
	v_cmp_lt_u32_e64 s[4:5], 16, v3
	v_subrev_u32_e32 v32, 17, v3
	s_addc_u32 s1, s85, 0
	s_lshl_b32 s12, s15, 3
	s_lshl_b32 s13, s9, 3
	v_add_u32_e32 v33, v2, v5
	s_mov_b32 s14, 0x2067800
	v_mov_b32_e32 v34, 0xfe000000
	s_mov_b32 s8, 0x3e38aa3b
	s_branch .LBB0_579
